# GLA lower-bound loads: one warm-up load issued with the gate loads, then 16 L1-resident loads issued together
# speedup vs baseline: 1.0058x; 1.0058x over previous
.LBB0_595:
	s_mul_hi_i32 s0, s8, 0x3e0f83e1
	s_lshr_b32 s1, s0, 31
	s_ashr_i32 s0, s0, 5
	s_add_i32 s0, s0, s1
	s_mul_i32 s1, s0, 0x84
	s_sub_i32 s20, s8, s1
	s_and_b32 s19, s0, 1
	s_bfe_u32 s21, s0, 0x20001
	s_lshl_b32 s1, s20, 6
	s_cmp_lt_i32 s20, 4
	s_cselect_b32 s9, s7, s6
	v_mov_b32_e32 v16, v207
	s_add_i32 s9, s9, s1
	v_mov_b32_e32 v10, v207
	s_cmp_eq_u32 s19, 0
	s_barrier
	s_cselect_b64 s[42:43], -1, 0
	v_ashrrev_i32_e32 v4, 3, v10
	v_lshlrev_b32_e32 v0, 4, v10
	s_cmp_eq_u32 s19, 1
	v_and_b32_e32 v2, 0x70, v0
	v_add_u32_e32 v3, s9, v4
	v_mov_b64_e32 v[0:1], s[36:37]
	s_cselect_b64 s[2:3], -1, 0
	s_and_b32 s22, s0, -8
	v_mad_i64_i32 v[0:1], s[0:1], v3, s14, v[0:1]
	s_lshl_b32 s26, s21, 8
	s_lshl_b32 s18, s21, 7
	v_lshl_add_u64 v[0:1], v[0:1], 0, s[26:27]
	v_lshlrev_b32_e32 v128, 1, v2
	v_lshlrev_b32_e32 v3, 9, v4
	v_lshlrev_b32_e32 v5, 2, v2
	v_lshl_add_u64 v[0:1], v[0:1], 0, v[128:129]
	s_mov_b64 s[0:1], -1
	s_movk_i32 s100, 0xe00
	s_cmp_eq_u32 s22, 8
	s_cselect_b32 s100, 0x400, s100
	s_lshl_b32 s101, s21, 7
	s_add_i32 s100, s100, s101
	s_lshl_b32 s100, s100, 1
	s_mov_b32 s101, 0
	v_and_b32_e32 v162, 63, v207
	v_or_b32_e32 v162, s9, v162
	v_mul_u32_u24_e32 v162, 0x1200, v162
	v_mov_b32_e32 v163, 0
	v_lshl_add_u64 v[162:163], v[162:163], 1, s[36:37]
	v_lshl_add_u64 v[162:163], v[162:163], 0, s[100:101]
	v_ashrrev_i32_e32 v164, 2, v207
	v_and_b32_e32 v164, -16, v164
	v_mov_b32_e32 v165, 0
	v_lshl_add_u64 v[162:163], v[164:165], 1, v[162:163]
	global_load_dwordx4 v[154:157], v[162:163], off
	global_load_dwordx4 v[158:161], v[162:163], off offset:16
	s_cmp_lg_u32 s22, 8
	v_add3_u32 v5, 0, v3, v5
	s_cbranch_scc0 .LBB0_613
	s_and_b64 s[0:1], s[42:43], exec
	s_cselect_b32 s26, s15, 0x1800
	v_lshl_add_u64 v[12:13], v[0:1], 0, s[26:27]
	global_load_dwordx4 v[6:9], v[12:13], off
	global_load_dwordx4 v[26:29], v[12:13], off offset:16
	v_or_b32_e32 v2, s18, v2
	v_lshlrev_b32_e32 v128, 2, v2
	v_lshl_add_u64 v[2:3], s[78:79], 0, v[128:129]
	global_load_dword v246, v[2:3], off
	s_waitcnt vmcnt(0) lgkmcnt(0)
	v_lshlrev_b32_e32 v11, 16, v6
	v_and_b32_e32 v25, 0xffff0000, v6
	global_load_dword v6, v[2:3], off
	global_load_dword v182, v[2:3], off offset:4
	global_load_dword v183, v[2:3], off offset:8
	global_load_dword v184, v[2:3], off offset:12
	global_load_dword v185, v[2:3], off offset:16
	global_load_dword v186, v[2:3], off offset:20
	global_load_dword v187, v[2:3], off offset:24
	global_load_dword v188, v[2:3], off offset:28
	global_load_dword v189, v[2:3], off offset:32
	global_load_dword v190, v[2:3], off offset:36
	global_load_dword v191, v[2:3], off offset:40
	global_load_dword v238, v[2:3], off offset:44
	global_load_dword v239, v[2:3], off offset:48
	global_load_dword v240, v[2:3], off offset:52
	global_load_dword v241, v[2:3], off offset:56
	global_load_dword v242, v[2:3], off offset:60
	v_lshlrev_b32_e32 v15, 16, v8
	v_and_b32_e32 v12, 0xffff0000, v8
	v_mul_f32_e32 v8, 0xbfb8aa3b, v11
	v_exp_f32_e32 v8, v8
	v_lshlrev_b32_e32 v20, 16, v9
	v_and_b32_e32 v17, 0xffff0000, v9
	v_lshlrev_b32_e32 v24, 16, v26
	v_add_f32_e32 v8, 1.0, v8
	v_rcp_f32_e32 v11, v8
	v_and_b32_e32 v21, 0xffff0000, v26
	v_lshlrev_b32_e32 v23, 16, v27
	v_and_b32_e32 v22, 0xffff0000, v27
	v_lshlrev_b32_e32 v19, 16, v28
	v_and_b32_e32 v18, 0xffff0000, v28
	v_mul_f32_e32 v8, 1.0, v11
	v_mul_f32_e32 v9, 0xbfb8aa3b, v25
	v_exp_f32_e32 v9, v9
	v_lshlrev_b32_e32 v30, 16, v7
	v_and_b32_e32 v31, 0xffff0000, v7
	v_lshlrev_b32_e32 v14, 16, v29
	v_add_f32_e32 v9, 1.0, v9
	v_rcp_f32_e32 v25, v9
	v_and_b32_e32 v13, 0xffff0000, v29
	v_mul_f32_e32 v15, 0xbfb8aa3b, v15
	v_exp_f32_e32 v15, v15
	v_mul_f32_e32 v9, 1.0, v25
	v_mul_f32_e32 v11, 0xbfb8aa3b, v30
	v_exp_f32_e32 v11, v11
	v_add_f32_e32 v15, 1.0, v15
	v_mul_f32_e32 v12, 0xbfb8aa3b, v12
	v_exp_f32_e32 v12, v12
	v_add_f32_e32 v11, 1.0, v11
	v_mul_f32_e32 v20, 0xbfb8aa3b, v20
	v_exp_f32_e32 v20, v20
	v_add_f32_e32 v12, 1.0, v12
	v_mul_f32_e32 v17, 0xbfb8aa3b, v17
	v_exp_f32_e32 v17, v17
	v_add_f32_e32 v20, 1.0, v20
	v_mul_f32_e32 v24, 0xbfb8aa3b, v24
	v_exp_f32_e32 v24, v24
	v_add_f32_e32 v17, 1.0, v17
	v_mul_f32_e32 v21, 0xbfb8aa3b, v21
	v_exp_f32_e32 v21, v21
	v_add_f32_e32 v24, 1.0, v24
	v_mul_f32_e32 v23, 0xbfb8aa3b, v23
	v_exp_f32_e32 v23, v23
	v_add_f32_e32 v21, 1.0, v21
	v_mul_f32_e32 v22, 0xbfb8aa3b, v22
	v_exp_f32_e32 v22, v22
	v_add_f32_e32 v23, 1.0, v23
	v_mul_f32_e32 v19, 0xbfb8aa3b, v19
	v_exp_f32_e32 v19, v19
	v_add_f32_e32 v22, 1.0, v22
	v_mul_f32_e32 v18, 0xbfb8aa3b, v18
	v_exp_f32_e32 v18, v18
	v_add_f32_e32 v19, 1.0, v19
	v_mul_f32_e32 v14, 0xbfb8aa3b, v14
	s_waitcnt vmcnt(0) lgkmcnt(0)
	v_sub_f32_e32 v7, 1.0, v6
	v_fmac_f32_e32 v6, v7, v8
	v_cmp_gt_f32_e32 vcc, s12, v6
	v_add_f32_e32 v18, 1.0, v18
	v_exp_f32_e32 v14, v14
	v_cndmask_b32_e64 v7, 0, 32, vcc
	v_ldexp_f32 v7, v6, v7
	v_log_f32_e32 v7, v7
	v_add_f32_e32 v14, 1.0, v14
	v_mul_f32_e32 v13, 0xbfb8aa3b, v13
	v_exp_f32_e32 v13, v13
	v_mul_f32_e32 v8, 0x3f317217, v7
	v_fma_f32 v8, v7, s86, -v8
	v_fmac_f32_e32 v8, 0x3377d1cf, v7
	v_fmac_f32_e32 v8, 0x3f317217, v7
	v_cmp_lt_f32_e64 s[0:1], |v7|, s87
	v_add_f32_e32 v13, 1.0, v13
	s_nop 0
	v_cndmask_b32_e64 v7, v7, v8, s[0:1]
	v_cndmask_b32_e32 v8, 0, v231, vcc
	v_sub_f32_e32 v7, v7, v8
	ds_write_b32 v5, v7
	v_sub_f32_e32 v8, 1.0, v182
	v_fma_f32 v7, v8, v9, v182
	v_cmp_gt_f32_e32 vcc, s12, v7
	s_nop 1
	v_cndmask_b32_e64 v8, 0, 32, vcc
	v_ldexp_f32 v8, v7, v8
	v_log_f32_e32 v8, v8
	s_nop 0
	v_mul_f32_e32 v9, 0x3f317217, v8
	v_fma_f32 v9, v8, s86, -v9
	v_fmac_f32_e32 v9, 0x3377d1cf, v8
	v_fmac_f32_e32 v9, 0x3f317217, v8
	v_cmp_lt_f32_e64 s[0:1], |v8|, s87
	s_nop 1
	v_cndmask_b32_e64 v8, v8, v9, s[0:1]
	v_cndmask_b32_e32 v9, 0, v231, vcc
	v_sub_f32_e32 v8, v8, v9
	ds_write_b32 v5, v8 offset:4
	v_rcp_f32_e32 v26, v11
	v_sub_f32_e32 v9, 1.0, v183
	v_mul_f32_e32 v11, 1.0, v26
	v_mul_f32_e32 v25, 0xbfb8aa3b, v31
	v_exp_f32_e32 v25, v25
	v_fma_f32 v8, v11, v9, v183
	v_add_f32_e32 v25, 1.0, v25
	v_rcp_f32_e32 v27, v25
	s_nop 0
	v_cmp_gt_f32_e32 vcc, s12, v8
	v_mul_f32_e32 v25, 1.0, v27
	s_nop 0
	v_cndmask_b32_e64 v9, 0, 32, vcc
	v_ldexp_f32 v9, v8, v9
	v_log_f32_e32 v9, v9
	s_nop 0
	v_mul_f32_e32 v11, 0x3f317217, v9
	v_fma_f32 v11, v9, s86, -v11
	v_fmac_f32_e32 v11, 0x3377d1cf, v9
	v_fmac_f32_e32 v11, 0x3f317217, v9
	v_cmp_lt_f32_e64 s[0:1], |v9|, s87
	s_nop 1
	v_cndmask_b32_e64 v9, v9, v11, s[0:1]
	v_cndmask_b32_e32 v11, 0, v231, vcc
	v_sub_f32_e32 v9, v9, v11
	ds_write_b32 v5, v9 offset:8
	v_sub_f32_e32 v11, 1.0, v184
	v_fma_f32 v9, v25, v11, v184
	v_cmp_gt_f32_e32 vcc, s12, v9
	s_nop 1
	v_cndmask_b32_e64 v11, 0, 32, vcc
	v_ldexp_f32 v11, v9, v11
	v_log_f32_e32 v11, v11
	s_nop 0
	v_mul_f32_e32 v25, 0x3f317217, v11
	v_fma_f32 v25, v11, s86, -v25
	v_fmac_f32_e32 v25, 0x3377d1cf, v11
	v_fmac_f32_e32 v25, 0x3f317217, v11
	v_cmp_lt_f32_e64 s[0:1], |v11|, s87
	s_nop 1
	v_cndmask_b32_e64 v11, v11, v25, s[0:1]
	v_cndmask_b32_e32 v25, 0, v231, vcc
	v_sub_f32_e32 v11, v11, v25
	ds_write_b32 v5, v11 offset:12
	v_rcp_f32_e32 v27, v15
	v_sub_f32_e32 v25, 1.0, v185
	v_mul_f32_e32 v15, 1.0, v27
	v_rcp_f32_e32 v27, v12
	v_fma_f32 v11, v15, v25, v185
	v_cmp_gt_f32_e32 vcc, s12, v11
	v_mul_f32_e32 v26, 1.0, v27
	s_nop 0
	v_cndmask_b32_e64 v12, 0, 32, vcc
	v_ldexp_f32 v12, v11, v12
	v_log_f32_e32 v12, v12
	s_nop 0
	v_mul_f32_e32 v15, 0x3f317217, v12
	v_fma_f32 v15, v12, s86, -v15
	v_fmac_f32_e32 v15, 0x3377d1cf, v12
	v_fmac_f32_e32 v15, 0x3f317217, v12
	v_cmp_lt_f32_e64 s[0:1], |v12|, s87
	s_nop 1
	v_cndmask_b32_e64 v12, v12, v15, s[0:1]
	v_cndmask_b32_e32 v15, 0, v231, vcc
	v_sub_f32_e32 v12, v12, v15
	ds_write_b32 v5, v12 offset:16
	v_sub_f32_e32 v15, 1.0, v186
	v_fma_f32 v12, v26, v15, v186
	v_cmp_gt_f32_e32 vcc, s12, v12
	s_nop 1
	v_cndmask_b32_e64 v15, 0, 32, vcc
	v_ldexp_f32 v15, v12, v15
	v_log_f32_e32 v15, v15
	s_nop 0
	v_mul_f32_e32 v25, 0x3f317217, v15
	v_fma_f32 v25, v15, s86, -v25
	v_fmac_f32_e32 v25, 0x3377d1cf, v15
	v_fmac_f32_e32 v25, 0x3f317217, v15
	v_cmp_lt_f32_e64 s[0:1], |v15|, s87
	s_nop 1
	v_cndmask_b32_e64 v15, v15, v25, s[0:1]
	v_cndmask_b32_e32 v25, 0, v231, vcc
	v_sub_f32_e32 v15, v15, v25
	ds_write_b32 v5, v15 offset:20
	v_rcp_f32_e32 v27, v20
	v_sub_f32_e32 v25, 1.0, v187
	v_mul_f32_e32 v20, 1.0, v27
	v_rcp_f32_e32 v27, v17
	v_fma_f32 v15, v20, v25, v187
	v_cmp_gt_f32_e32 vcc, s12, v15
	v_mul_f32_e32 v26, 1.0, v27
	s_nop 0
	v_cndmask_b32_e64 v17, 0, 32, vcc
	v_ldexp_f32 v17, v15, v17
	v_log_f32_e32 v17, v17
	s_nop 0
	v_mul_f32_e32 v20, 0x3f317217, v17
	v_fma_f32 v20, v17, s86, -v20
	v_fmac_f32_e32 v20, 0x3377d1cf, v17
	v_fmac_f32_e32 v20, 0x3f317217, v17
	v_cmp_lt_f32_e64 s[0:1], |v17|, s87
	s_nop 1
	v_cndmask_b32_e64 v17, v17, v20, s[0:1]
	v_cndmask_b32_e32 v20, 0, v231, vcc
	v_sub_f32_e32 v17, v17, v20
	ds_write_b32 v5, v17 offset:24
	v_sub_f32_e32 v20, 1.0, v188
	v_fma_f32 v17, v26, v20, v188
	v_cmp_gt_f32_e32 vcc, s12, v17
	s_nop 1
	v_cndmask_b32_e64 v20, 0, 32, vcc
	v_ldexp_f32 v20, v17, v20
	v_log_f32_e32 v20, v20
	s_nop 0
	v_mul_f32_e32 v25, 0x3f317217, v20
	v_fma_f32 v25, v20, s86, -v25
	v_fmac_f32_e32 v25, 0x3377d1cf, v20
	v_fmac_f32_e32 v25, 0x3f317217, v20
	v_cmp_lt_f32_e64 s[0:1], |v20|, s87
	s_nop 1
	v_cndmask_b32_e64 v20, v20, v25, s[0:1]
	v_cndmask_b32_e32 v25, 0, v231, vcc
	v_sub_f32_e32 v20, v20, v25
	ds_write_b32 v5, v20 offset:28
	v_rcp_f32_e32 v27, v24
	v_sub_f32_e32 v25, 1.0, v189
	v_mul_f32_e32 v24, 1.0, v27
	v_rcp_f32_e32 v27, v21
	v_fma_f32 v20, v24, v25, v189
	v_cmp_gt_f32_e32 vcc, s12, v20
	v_mul_f32_e32 v26, 1.0, v27
	s_nop 0
	v_cndmask_b32_e64 v21, 0, 32, vcc
	v_ldexp_f32 v21, v20, v21
	v_log_f32_e32 v21, v21
	s_nop 0
	v_mul_f32_e32 v24, 0x3f317217, v21
	v_fma_f32 v24, v21, s86, -v24
	v_fmac_f32_e32 v24, 0x3377d1cf, v21
	v_fmac_f32_e32 v24, 0x3f317217, v21
	v_cmp_lt_f32_e64 s[0:1], |v21|, s87
	s_nop 1
	v_cndmask_b32_e64 v21, v21, v24, s[0:1]
	v_cndmask_b32_e32 v24, 0, v231, vcc
	v_sub_f32_e32 v21, v21, v24
	ds_write_b32 v5, v21 offset:32
	v_sub_f32_e32 v24, 1.0, v190
	v_fma_f32 v21, v26, v24, v190
	v_cmp_gt_f32_e32 vcc, s12, v21
	s_nop 1
	v_cndmask_b32_e64 v24, 0, 32, vcc
	v_ldexp_f32 v24, v21, v24
	v_log_f32_e32 v24, v24
	s_nop 0
	v_mul_f32_e32 v25, 0x3f317217, v24
	v_fma_f32 v25, v24, s86, -v25
	v_fmac_f32_e32 v25, 0x3377d1cf, v24
	v_fmac_f32_e32 v25, 0x3f317217, v24
	v_cmp_lt_f32_e64 s[0:1], |v24|, s87
	s_nop 1
	v_cndmask_b32_e64 v24, v24, v25, s[0:1]
	v_cndmask_b32_e32 v25, 0, v231, vcc
	v_sub_f32_e32 v24, v24, v25
	ds_write_b32 v5, v24 offset:36
	v_rcp_f32_e32 v27, v23
	v_sub_f32_e32 v25, 1.0, v191
	v_mul_f32_e32 v23, 1.0, v27
	v_rcp_f32_e32 v27, v22
	v_fma_f32 v24, v23, v25, v191
	v_cmp_gt_f32_e32 vcc, s12, v24
	v_mul_f32_e32 v26, 1.0, v27
	s_nop 0
	v_cndmask_b32_e64 v22, 0, 32, vcc
	v_ldexp_f32 v22, v24, v22
	v_log_f32_e32 v22, v22
	s_nop 0
	v_mul_f32_e32 v23, 0x3f317217, v22
	v_fma_f32 v23, v22, s86, -v23
	v_fmac_f32_e32 v23, 0x3377d1cf, v22
	v_fmac_f32_e32 v23, 0x3f317217, v22
	v_cmp_lt_f32_e64 s[0:1], |v22|, s87
	s_nop 1
	v_cndmask_b32_e64 v22, v22, v23, s[0:1]
	v_cndmask_b32_e32 v23, 0, v231, vcc
	v_sub_f32_e32 v22, v22, v23
	ds_write_b32 v5, v22 offset:40
	v_sub_f32_e32 v23, 1.0, v238
	v_fma_f32 v22, v26, v23, v238
	v_cmp_gt_f32_e32 vcc, s12, v22
	s_nop 1
	v_cndmask_b32_e64 v23, 0, 32, vcc
	v_ldexp_f32 v23, v22, v23
	v_log_f32_e32 v23, v23
	s_nop 0
	v_mul_f32_e32 v25, 0x3f317217, v23
	v_fma_f32 v25, v23, s86, -v25
	v_fmac_f32_e32 v25, 0x3377d1cf, v23
	v_fmac_f32_e32 v25, 0x3f317217, v23
	v_cmp_lt_f32_e64 s[0:1], |v23|, s87
	s_nop 1
	v_cndmask_b32_e64 v23, v23, v25, s[0:1]
	v_cndmask_b32_e32 v25, 0, v231, vcc
	v_sub_f32_e32 v23, v23, v25
	ds_write_b32 v5, v23 offset:44
	v_rcp_f32_e32 v27, v19
	v_sub_f32_e32 v25, 1.0, v239
	v_mul_f32_e32 v19, 1.0, v27
	v_rcp_f32_e32 v27, v18
	v_fma_f32 v23, v19, v25, v239
	v_cmp_gt_f32_e32 vcc, s12, v23
	v_mul_f32_e32 v26, 1.0, v27
	s_nop 0
	v_cndmask_b32_e64 v18, 0, 32, vcc
	v_ldexp_f32 v18, v23, v18
	v_log_f32_e32 v18, v18
	s_nop 0
	v_mul_f32_e32 v19, 0x3f317217, v18
	v_fma_f32 v19, v18, s86, -v19
	v_fmac_f32_e32 v19, 0x3377d1cf, v18
	v_fmac_f32_e32 v19, 0x3f317217, v18
	v_cmp_lt_f32_e64 s[0:1], |v18|, s87
	s_nop 1
	v_cndmask_b32_e64 v18, v18, v19, s[0:1]
	v_cndmask_b32_e32 v19, 0, v231, vcc
	v_sub_f32_e32 v18, v18, v19
	ds_write_b32 v5, v18 offset:48
	v_sub_f32_e32 v19, 1.0, v240
	v_fma_f32 v18, v26, v19, v240
	v_cmp_gt_f32_e32 vcc, s12, v18
	s_nop 1
	v_cndmask_b32_e64 v19, 0, 32, vcc
	v_ldexp_f32 v19, v18, v19
	v_log_f32_e32 v19, v19
	s_nop 0
	v_mul_f32_e32 v25, 0x3f317217, v19
	v_fma_f32 v25, v19, s86, -v25
	v_fmac_f32_e32 v25, 0x3377d1cf, v19
	v_fmac_f32_e32 v25, 0x3f317217, v19
	v_cmp_lt_f32_e64 s[0:1], |v19|, s87
	s_nop 1
	v_cndmask_b32_e64 v19, v19, v25, s[0:1]
	v_cndmask_b32_e32 v25, 0, v231, vcc
	v_sub_f32_e32 v19, v19, v25
	ds_write_b32 v5, v19 offset:52
	v_rcp_f32_e32 v27, v14
	v_sub_f32_e32 v19, 1.0, v241
	v_mul_f32_e32 v14, 1.0, v27
	v_rcp_f32_e32 v27, v13
	v_fma_f32 v25, v14, v19, v241
	v_cmp_gt_f32_e32 vcc, s12, v25
	v_mul_f32_e32 v13, 1.0, v27
	s_nop 0
	v_cndmask_b32_e64 v14, 0, 32, vcc
	v_ldexp_f32 v14, v25, v14
	v_log_f32_e32 v14, v14
	s_nop 0
	v_mul_f32_e32 v19, 0x3f317217, v14
	v_fma_f32 v19, v14, s86, -v19
	v_fmac_f32_e32 v19, 0x3377d1cf, v14
	v_fmac_f32_e32 v19, 0x3f317217, v14
	v_cmp_lt_f32_e64 s[0:1], |v14|, s87
	s_nop 1
	v_cndmask_b32_e64 v14, v14, v19, s[0:1]
	v_cndmask_b32_e32 v19, 0, v231, vcc
	v_sub_f32_e32 v14, v14, v19
	ds_write_b32 v5, v14 offset:56
	v_sub_f32_e32 v2, 1.0, v242
	v_fma_f32 v3, v13, v2, v242
	v_cmp_gt_f32_e32 vcc, s12, v3
	s_nop 1
	v_cndmask_b32_e64 v2, 0, 32, vcc
	v_ldexp_f32 v2, v3, v2
	v_log_f32_e32 v2, v2
	s_nop 0
	v_mul_f32_e32 v13, 0x3f317217, v2
	v_fma_f32 v13, v2, s86, -v13
	v_fmac_f32_e32 v13, 0x3377d1cf, v2
	v_fmac_f32_e32 v13, 0x3f317217, v2
	v_cmp_lt_f32_e64 s[0:1], |v2|, s87
	s_nop 1
	v_cndmask_b32_e64 v2, v2, v13, s[0:1]
	v_cndmask_b32_e32 v13, 0, v231, vcc
	v_sub_f32_e32 v2, v2, v13
	v_ashrrev_i32_e32 v13, 7, v10
	v_and_b32_e32 v10, 0x7f, v10
	v_lshlrev_b32_e32 v14, 13, v13
	v_lshlrev_b32_e32 v19, 2, v10
	ds_write_b32 v5, v2 offset:60
	v_add3_u32 v2, 0, v19, v14
	s_mov_b64 s[0:1], -1
	s_and_b64 vcc, exec, s[2:3]
	s_waitcnt lgkmcnt(0)
	s_barrier
	s_cbranch_vccz .LBB0_598
	ds_read2st64_b32 v[166:167], v2 offset0:28 offset1:30
	ds_read2st64_b32 v[168:169], v2 offset0:24 offset1:26
	ds_read2st64_b32 v[170:171], v2 offset0:20 offset1:22
	ds_read2st64_b32 v[172:173], v2 offset0:16 offset1:18
	ds_read2st64_b32 v[174:175], v2 offset0:12 offset1:14
	ds_read2st64_b32 v[176:177], v2 offset0:8 offset1:10
	ds_read2st64_b32 v[178:179], v2 offset0:4 offset1:6
	ds_read2st64_b32 v[180:181], v2 offset1:2
	s_mov_b64 s[0:1], 0
	s_waitcnt lgkmcnt(0)
	v_add_f32_e32 v27, 0, v167
	v_add_f32_e32 v28, v27, v166
	ds_write2st64_b32 v2, v28, v27 offset0:28 offset1:30
	v_add_f32_e32 v27, v28, v169
	v_add_f32_e32 v28, v27, v168
	ds_write2st64_b32 v2, v28, v27 offset0:24 offset1:26
	v_add_f32_e32 v27, v28, v171
	v_add_f32_e32 v28, v27, v170
	ds_write2st64_b32 v2, v28, v27 offset0:20 offset1:22
	v_add_f32_e32 v27, v28, v173
	v_add_f32_e32 v28, v27, v172
	ds_write2st64_b32 v2, v28, v27 offset0:16 offset1:18
	v_add_f32_e32 v27, v28, v175
	v_add_f32_e32 v28, v27, v174
	ds_write2st64_b32 v2, v28, v27 offset0:12 offset1:14
	v_add_f32_e32 v27, v28, v177
	v_add_f32_e32 v28, v27, v176
	ds_write2st64_b32 v2, v28, v27 offset0:8 offset1:10
	v_add_f32_e32 v27, v28, v179
	v_add_f32_e32 v28, v27, v178
	ds_write2st64_b32 v2, v28, v27 offset0:4 offset1:6
	v_add_f32_e32 v27, v28, v181
	v_add_f32_e32 v26, v27, v180
	ds_write2st64_b32 v2, v26, v27 offset1:2

.LBB0_736:
	s_xor_b64 s[18:19], s[92:93], -1
	s_or_b32 s0, s95, s23
	s_mul_hi_i32 s8, s0, 0x84
	s_mul_i32 s9, s0, 0x84
	s_and_b64 s[0:1], s[92:93], exec
	s_cselect_b32 s0, s21, s94
	s_ashr_i32 s1, s0, 31
	s_add_u32 s0, s9, s0
	s_addc_u32 s1, s8, s1
	s_lshl_b64 s[0:1], s[0:1], 15
	v_lshl_add_u64 v[16:17], v[86:87], 0, s[0:1]
	global_load_dwordx4 v[60:63], v[16:17], off
	global_load_dwordx4 v[56:59], v[16:17], off offset:32
	global_load_dwordx4 v[52:55], v[16:17], off offset:64
	global_load_dwordx4 v[48:51], v[16:17], off offset:96
	global_load_dwordx4 v[44:47], v[16:17], off offset:128
	global_load_dwordx4 v[40:43], v[16:17], off offset:160
	global_load_dwordx4 v[36:39], v[16:17], off offset:192
	global_load_dwordx4 v[32:35], v[16:17], off offset:224
	v_mov_b32_e32 v113, v207
	s_and_b64 vcc, exec, s[96:97]
	v_ashrrev_i32_e32 v110, 3, v113
	v_lshlrev_b32_e32 v16, 4, v113
	v_and_b32_e32 v111, 0x70, v16
	v_add_u32_e32 v18, s22, v110
	v_mov_b64_e32 v[16:17], s[2:3]
	v_mad_i64_i32 v[16:17], s[0:1], v18, s14, v[16:17]
	v_lshlrev_b32_e32 v128, 1, v111
	v_lshl_add_u64 v[90:91], v[16:17], 0, v[128:129]
	v_lshlrev_b32_e32 v16, 9, v110
	v_lshlrev_b32_e32 v17, 2, v111
	v_add3_u32 v109, 0, v16, v17
	s_mov_b64 s[0:1], -1
	s_cbranch_vccz .LBB0_754
	s_and_b64 s[0:1], s[92:93], exec
	s_cselect_b32 s26, s15, 0x1800
	v_lshl_add_u64 v[20:21], v[90:91], 0, s[26:27]
	global_load_dwordx4 v[16:19], v[20:21], off
	global_load_dwordx4 v[116:119], v[20:21], off offset:16
	v_or_b32_e32 v243, s20, v111
	v_lshlrev_b32_e32 v244, 2, v243
	v_mov_b32_e32 v245, 0
	v_lshl_add_u64 v[244:245], s[78:79], 0, v[244:245]
	global_load_dword v246, v[244:245], off
	s_waitcnt vmcnt(0) lgkmcnt(0)
	v_lshlrev_b32_e32 v20, 16, v16
	v_and_b32_e32 v112, 0xffff0000, v16
	v_or_b32_e32 v16, s20, v111
	v_lshlrev_b32_e32 v128, 2, v16
	v_lshlrev_b32_e32 v115, 16, v17
	v_and_b32_e32 v120, 0xffff0000, v17
	v_lshl_add_u64 v[16:17], s[78:79], 0, v[128:129]
	global_load_dword v111, v[16:17], off
	global_load_dword v182, v[16:17], off offset:4
	global_load_dword v183, v[16:17], off offset:8
	global_load_dword v184, v[16:17], off offset:12
	global_load_dword v185, v[16:17], off offset:16
	global_load_dword v186, v[16:17], off offset:20
	global_load_dword v187, v[16:17], off offset:24
	global_load_dword v188, v[16:17], off offset:28
	global_load_dword v189, v[16:17], off offset:32
	global_load_dword v190, v[16:17], off offset:36
	global_load_dword v191, v[16:17], off offset:40
	global_load_dword v238, v[16:17], off offset:44
	global_load_dword v239, v[16:17], off offset:48
	global_load_dword v240, v[16:17], off offset:52
	global_load_dword v241, v[16:17], off offset:56
	global_load_dword v242, v[16:17], off offset:60
	v_lshlrev_b32_e32 v31, 16, v19
	v_and_b32_e32 v30, 0xffff0000, v19
	v_mul_f32_e32 v19, 0xbfb8aa3b, v20
	v_exp_f32_e32 v19, v19
	v_lshlrev_b32_e32 v29, 16, v116
	v_and_b32_e32 v28, 0xffff0000, v116
	v_lshlrev_b32_e32 v27, 16, v117
	v_add_f32_e32 v19, 1.0, v19
	v_rcp_f32_e32 v116, v19
	v_and_b32_e32 v26, 0xffff0000, v117
	v_lshlrev_b32_e32 v25, 16, v118
	v_and_b32_e32 v24, 0xffff0000, v118
	v_lshlrev_b32_e32 v23, 16, v119
	v_and_b32_e32 v22, 0xffff0000, v119
	v_mul_f32_e32 v19, 1.0, v116
	v_mul_f32_e32 v20, 0xbfb8aa3b, v112
	v_exp_f32_e32 v20, v20
	v_lshlrev_b32_e32 v114, 16, v18
	v_and_b32_e32 v21, 0xffff0000, v18
	v_mul_f32_e32 v114, 0xbfb8aa3b, v114
	v_add_f32_e32 v20, 1.0, v20
	v_rcp_f32_e32 v116, v20
	v_exp_f32_e32 v114, v114
	v_mul_f32_e32 v21, 0xbfb8aa3b, v21
	v_exp_f32_e32 v21, v21
	v_mul_f32_e32 v20, 1.0, v116
	v_add_f32_e32 v114, 1.0, v114
	v_add_f32_e32 v21, 1.0, v21
	v_mul_f32_e32 v31, 0xbfb8aa3b, v31
	v_exp_f32_e32 v31, v31
	v_mul_f32_e32 v30, 0xbfb8aa3b, v30
	v_exp_f32_e32 v30, v30
	v_mul_f32_e32 v29, 0xbfb8aa3b, v29
	v_add_f32_e32 v31, 1.0, v31
	v_exp_f32_e32 v29, v29
	v_add_f32_e32 v30, 1.0, v30
	v_mul_f32_e32 v28, 0xbfb8aa3b, v28
	v_exp_f32_e32 v28, v28
	v_add_f32_e32 v29, 1.0, v29
	v_mul_f32_e32 v27, 0xbfb8aa3b, v27
	v_exp_f32_e32 v27, v27
	v_add_f32_e32 v28, 1.0, v28
	v_mul_f32_e32 v26, 0xbfb8aa3b, v26
	v_exp_f32_e32 v26, v26
	v_add_f32_e32 v27, 1.0, v27
	v_mul_f32_e32 v25, 0xbfb8aa3b, v25
	v_exp_f32_e32 v25, v25
	v_add_f32_e32 v26, 1.0, v26
	v_mul_f32_e32 v24, 0xbfb8aa3b, v24
	v_exp_f32_e32 v24, v24
	v_add_f32_e32 v25, 1.0, v25
	v_mul_f32_e32 v23, 0xbfb8aa3b, v23
	v_exp_f32_e32 v23, v23
	v_add_f32_e32 v24, 1.0, v24
	v_mul_f32_e32 v22, 0xbfb8aa3b, v22
	v_exp_f32_e32 v22, v22
	v_add_f32_e32 v23, 1.0, v23
	s_waitcnt vmcnt(0) lgkmcnt(0)
	v_sub_f32_e32 v18, 1.0, v111
	v_fmac_f32_e32 v111, v18, v19
	v_cmp_gt_f32_e32 vcc, s12, v111
	v_add_f32_e32 v22, 1.0, v22
	s_nop 0
	v_cndmask_b32_e64 v18, 0, 32, vcc
	v_ldexp_f32 v18, v111, v18
	v_log_f32_e32 v18, v18
	s_nop 0
	v_mul_f32_e32 v19, 0x3f317217, v18
	v_fma_f32 v19, v18, s86, -v19
	v_fmac_f32_e32 v19, 0x3377d1cf, v18
	v_fmac_f32_e32 v19, 0x3f317217, v18
	v_cmp_lt_f32_e64 s[0:1], |v18|, s87
	s_nop 1
	v_cndmask_b32_e64 v18, v18, v19, s[0:1]
	v_cndmask_b32_e32 v19, 0, v231, vcc
	v_sub_f32_e32 v18, v18, v19
	ds_write_b32 v109, v18
	v_sub_f32_e32 v18, 1.0, v182
	v_fma_f32 v112, v18, v20, v182
	v_cmp_gt_f32_e32 vcc, s12, v112
	v_mul_f32_e32 v20, 0xbfb8aa3b, v115
	v_exp_f32_e32 v20, v20
	v_cndmask_b32_e64 v18, 0, 32, vcc
	v_ldexp_f32 v18, v112, v18
	v_log_f32_e32 v18, v18
	v_add_f32_e32 v20, 1.0, v20
	v_mul_f32_e32 v19, 0x3f317217, v18
	v_fma_f32 v19, v18, s86, -v19
	v_fmac_f32_e32 v19, 0x3377d1cf, v18
	v_fmac_f32_e32 v19, 0x3f317217, v18
	v_cmp_lt_f32_e64 s[0:1], |v18|, s87
	s_nop 1
	v_cndmask_b32_e64 v18, v18, v19, s[0:1]
	v_cndmask_b32_e32 v19, 0, v231, vcc
	v_sub_f32_e32 v18, v18, v19
	ds_write_b32 v109, v18 offset:4
	v_rcp_f32_e32 v116, v20
	v_sub_f32_e32 v19, 1.0, v183
	v_mul_f32_e32 v20, 1.0, v116
	v_mul_f32_e32 v115, 0xbfb8aa3b, v120
	v_exp_f32_e32 v115, v115
	v_fma_f32 v18, v20, v19, v183
	v_add_f32_e32 v115, 1.0, v115
	v_rcp_f32_e32 v117, v115
	s_nop 0
	v_cmp_gt_f32_e32 vcc, s12, v18
	v_mul_f32_e32 v115, 1.0, v117
	s_nop 0
	v_cndmask_b32_e64 v19, 0, 32, vcc
	v_ldexp_f32 v19, v18, v19
	v_log_f32_e32 v19, v19
	s_nop 0
	v_mul_f32_e32 v20, 0x3f317217, v19
	v_fma_f32 v20, v19, s86, -v20
	v_fmac_f32_e32 v20, 0x3377d1cf, v19
	v_fmac_f32_e32 v20, 0x3f317217, v19
	v_cmp_lt_f32_e64 s[0:1], |v19|, s87
	s_nop 1
	v_cndmask_b32_e64 v19, v19, v20, s[0:1]
	v_cndmask_b32_e32 v20, 0, v231, vcc
	v_sub_f32_e32 v19, v19, v20
	ds_write_b32 v109, v19 offset:8
	v_sub_f32_e32 v20, 1.0, v184
	v_fma_f32 v19, v115, v20, v184
	v_cmp_gt_f32_e32 vcc, s12, v19
	s_nop 1
	v_cndmask_b32_e64 v20, 0, 32, vcc
	v_ldexp_f32 v20, v19, v20
	v_log_f32_e32 v20, v20
	s_nop 0
	v_mul_f32_e32 v115, 0x3f317217, v20
	v_fma_f32 v115, v20, s86, -v115
	v_fmac_f32_e32 v115, 0x3377d1cf, v20
	v_fmac_f32_e32 v115, 0x3f317217, v20
	v_cmp_lt_f32_e64 s[0:1], |v20|, s87
	s_nop 1
	v_cndmask_b32_e64 v20, v20, v115, s[0:1]
	v_cndmask_b32_e32 v115, 0, v231, vcc
	v_sub_f32_e32 v20, v20, v115
	ds_write_b32 v109, v20 offset:12
	v_rcp_f32_e32 v117, v114
	v_sub_f32_e32 v115, 1.0, v185
	v_mul_f32_e32 v114, 1.0, v117
	v_rcp_f32_e32 v117, v21
	v_fma_f32 v20, v114, v115, v185
	v_cmp_gt_f32_e32 vcc, s12, v20
	v_mul_f32_e32 v116, 1.0, v117
	s_nop 0
	v_cndmask_b32_e64 v21, 0, 32, vcc
	v_ldexp_f32 v21, v20, v21
	v_log_f32_e32 v21, v21
	s_nop 0
	v_mul_f32_e32 v114, 0x3f317217, v21
	v_fma_f32 v114, v21, s86, -v114
	v_fmac_f32_e32 v114, 0x3377d1cf, v21
	v_fmac_f32_e32 v114, 0x3f317217, v21
	v_cmp_lt_f32_e64 s[0:1], |v21|, s87
	s_nop 1
	v_cndmask_b32_e64 v21, v21, v114, s[0:1]
	v_cndmask_b32_e32 v114, 0, v231, vcc
	v_sub_f32_e32 v21, v21, v114
	ds_write_b32 v109, v21 offset:16
	v_sub_f32_e32 v114, 1.0, v186
	v_fma_f32 v21, v116, v114, v186
	v_cmp_gt_f32_e32 vcc, s12, v21
	s_nop 1
	v_cndmask_b32_e64 v114, 0, 32, vcc
	v_ldexp_f32 v114, v21, v114
	v_log_f32_e32 v114, v114
	s_nop 0
	v_mul_f32_e32 v115, 0x3f317217, v114
	v_fma_f32 v115, v114, s86, -v115
	v_fmac_f32_e32 v115, 0x3377d1cf, v114
	v_fmac_f32_e32 v115, 0x3f317217, v114
	v_cmp_lt_f32_e64 s[0:1], |v114|, s87
	s_nop 1
	v_cndmask_b32_e64 v114, v114, v115, s[0:1]
	v_cndmask_b32_e32 v115, 0, v231, vcc
	v_sub_f32_e32 v114, v114, v115
	ds_write_b32 v109, v114 offset:20
	v_rcp_f32_e32 v117, v31
	v_sub_f32_e32 v115, 1.0, v187
	v_mul_f32_e32 v31, 1.0, v117
	v_rcp_f32_e32 v117, v30
	v_fma_f32 v114, v31, v115, v187
	v_cmp_gt_f32_e32 vcc, s12, v114
	v_mul_f32_e32 v30, 1.0, v117
	s_nop 0
	v_cndmask_b32_e64 v31, 0, 32, vcc
	v_ldexp_f32 v31, v114, v31
	v_log_f32_e32 v31, v31
	s_nop 0
	v_mul_f32_e32 v115, 0x3f317217, v31
	v_fma_f32 v115, v31, s86, -v115
	v_fmac_f32_e32 v115, 0x3377d1cf, v31
	v_fmac_f32_e32 v115, 0x3f317217, v31
	v_cmp_lt_f32_e64 s[0:1], |v31|, s87
	s_nop 1
	v_cndmask_b32_e64 v31, v31, v115, s[0:1]
	v_cndmask_b32_e32 v115, 0, v231, vcc
	v_sub_f32_e32 v31, v31, v115
	ds_write_b32 v109, v31 offset:24
	v_sub_f32_e32 v31, 1.0, v188
	v_fma_f32 v115, v30, v31, v188
	v_cmp_gt_f32_e32 vcc, s12, v115
	s_nop 1
	v_cndmask_b32_e64 v30, 0, 32, vcc
	v_ldexp_f32 v30, v115, v30
	v_log_f32_e32 v30, v30
	s_nop 0
	v_mul_f32_e32 v31, 0x3f317217, v30
	v_fma_f32 v31, v30, s86, -v31
	v_fmac_f32_e32 v31, 0x3377d1cf, v30
	v_fmac_f32_e32 v31, 0x3f317217, v30
	v_cmp_lt_f32_e64 s[0:1], |v30|, s87
	s_nop 1
	v_cndmask_b32_e64 v30, v30, v31, s[0:1]
	v_cndmask_b32_e32 v31, 0, v231, vcc
	v_sub_f32_e32 v30, v30, v31
	ds_write_b32 v109, v30 offset:28
	v_rcp_f32_e32 v117, v29
	v_sub_f32_e32 v30, 1.0, v189
	v_mul_f32_e32 v29, 1.0, v117
	v_rcp_f32_e32 v117, v28
	v_fma_f32 v116, v29, v30, v189
	v_cmp_gt_f32_e32 vcc, s12, v116
	v_mul_f32_e32 v28, 1.0, v117
	s_nop 0
	v_cndmask_b32_e64 v29, 0, 32, vcc
	v_ldexp_f32 v29, v116, v29
	v_log_f32_e32 v29, v29
	s_nop 0
	v_mul_f32_e32 v30, 0x3f317217, v29
	v_fma_f32 v30, v29, s86, -v30
	v_fmac_f32_e32 v30, 0x3377d1cf, v29
	v_fmac_f32_e32 v30, 0x3f317217, v29
	v_cmp_lt_f32_e64 s[0:1], |v29|, s87
	s_nop 1
	v_cndmask_b32_e64 v29, v29, v30, s[0:1]
	v_cndmask_b32_e32 v30, 0, v231, vcc
	v_sub_f32_e32 v29, v29, v30
	ds_write_b32 v109, v29 offset:32
	v_sub_f32_e32 v29, 1.0, v190
	v_fma_f32 v117, v28, v29, v190
	v_cmp_gt_f32_e32 vcc, s12, v117
	s_nop 1
	v_cndmask_b32_e64 v28, 0, 32, vcc
	v_ldexp_f32 v28, v117, v28
	v_log_f32_e32 v28, v28
	s_nop 0
	v_mul_f32_e32 v29, 0x3f317217, v28
	v_fma_f32 v29, v28, s86, -v29
	v_fmac_f32_e32 v29, 0x3377d1cf, v28
	v_fmac_f32_e32 v29, 0x3f317217, v28
	v_cmp_lt_f32_e64 s[0:1], |v28|, s87
	s_nop 1
	v_cndmask_b32_e64 v28, v28, v29, s[0:1]
	v_cndmask_b32_e32 v29, 0, v231, vcc
	v_sub_f32_e32 v28, v28, v29
	ds_write_b32 v109, v28 offset:36
	v_rcp_f32_e32 v30, v27
	v_sub_f32_e32 v28, 1.0, v191
	v_mul_f32_e32 v27, 1.0, v30
	v_rcp_f32_e32 v30, v26
	v_fma_f32 v118, v27, v28, v191
	v_cmp_gt_f32_e32 vcc, s12, v118
	v_mul_f32_e32 v29, 1.0, v30
	s_nop 0
	v_cndmask_b32_e64 v26, 0, 32, vcc
	v_ldexp_f32 v26, v118, v26
	v_log_f32_e32 v26, v26
	s_nop 0
	v_mul_f32_e32 v27, 0x3f317217, v26
	v_fma_f32 v27, v26, s86, -v27
	v_fmac_f32_e32 v27, 0x3377d1cf, v26
	v_fmac_f32_e32 v27, 0x3f317217, v26
	v_cmp_lt_f32_e64 s[0:1], |v26|, s87
	s_nop 1
	v_cndmask_b32_e64 v26, v26, v27, s[0:1]
	v_cndmask_b32_e32 v27, 0, v231, vcc
	v_sub_f32_e32 v26, v26, v27
	ds_write_b32 v109, v26 offset:40
	v_sub_f32_e32 v27, 1.0, v238
	v_fma_f32 v26, v29, v27, v238
	v_cmp_gt_f32_e32 vcc, s12, v26
	s_nop 1
	v_cndmask_b32_e64 v27, 0, 32, vcc
	v_ldexp_f32 v27, v26, v27
	v_log_f32_e32 v27, v27
	s_nop 0
	v_mul_f32_e32 v28, 0x3f317217, v27
	v_fma_f32 v28, v27, s86, -v28
	v_fmac_f32_e32 v28, 0x3377d1cf, v27
	v_fmac_f32_e32 v28, 0x3f317217, v27
	v_cmp_lt_f32_e64 s[0:1], |v27|, s87
	s_nop 1
	v_cndmask_b32_e64 v27, v27, v28, s[0:1]
	v_cndmask_b32_e32 v28, 0, v231, vcc
	v_sub_f32_e32 v27, v27, v28
	ds_write_b32 v109, v27 offset:44
	v_rcp_f32_e32 v30, v25
	v_sub_f32_e32 v28, 1.0, v239
	v_mul_f32_e32 v25, 1.0, v30
	v_rcp_f32_e32 v30, v24
	v_fma_f32 v27, v25, v28, v239
	v_cmp_gt_f32_e32 vcc, s12, v27
	v_mul_f32_e32 v29, 1.0, v30
	s_nop 0
	v_cndmask_b32_e64 v24, 0, 32, vcc
	v_ldexp_f32 v24, v27, v24
	v_log_f32_e32 v24, v24
	s_nop 0
	v_mul_f32_e32 v25, 0x3f317217, v24
	v_fma_f32 v25, v24, s86, -v25
	v_fmac_f32_e32 v25, 0x3377d1cf, v24
	v_fmac_f32_e32 v25, 0x3f317217, v24
	v_cmp_lt_f32_e64 s[0:1], |v24|, s87
	s_nop 1
	v_cndmask_b32_e64 v24, v24, v25, s[0:1]
	v_cndmask_b32_e32 v25, 0, v231, vcc
	v_sub_f32_e32 v24, v24, v25
	ds_write_b32 v109, v24 offset:48
	v_sub_f32_e32 v25, 1.0, v240
	v_fma_f32 v24, v29, v25, v240
	v_cmp_gt_f32_e32 vcc, s12, v24
	s_nop 1
	v_cndmask_b32_e64 v25, 0, 32, vcc
	v_ldexp_f32 v25, v24, v25
	v_log_f32_e32 v25, v25
	s_nop 0
	v_mul_f32_e32 v28, 0x3f317217, v25
	v_fma_f32 v28, v25, s86, -v28
	v_fmac_f32_e32 v28, 0x3377d1cf, v25
	v_fmac_f32_e32 v28, 0x3f317217, v25
	v_cmp_lt_f32_e64 s[0:1], |v25|, s87
	s_nop 1
	v_cndmask_b32_e64 v25, v25, v28, s[0:1]
	v_cndmask_b32_e32 v28, 0, v231, vcc
	v_sub_f32_e32 v25, v25, v28
	ds_write_b32 v109, v25 offset:52
	v_rcp_f32_e32 v30, v23
	v_sub_f32_e32 v28, 1.0, v241
	v_mul_f32_e32 v23, 1.0, v30
	v_rcp_f32_e32 v30, v22
	v_fma_f32 v25, v23, v28, v241
	v_cmp_gt_f32_e32 vcc, s12, v25
	v_mul_f32_e32 v22, 1.0, v30
	s_nop 0
	v_cndmask_b32_e64 v23, 0, 32, vcc
	v_ldexp_f32 v23, v25, v23
	v_log_f32_e32 v23, v23
	s_nop 0
	v_mul_f32_e32 v28, 0x3f317217, v23
	v_fma_f32 v28, v23, s86, -v28
	v_fmac_f32_e32 v28, 0x3377d1cf, v23
	v_fmac_f32_e32 v28, 0x3f317217, v23
	v_cmp_lt_f32_e64 s[0:1], |v23|, s87
	s_nop 1
	v_cndmask_b32_e64 v23, v23, v28, s[0:1]
	v_cndmask_b32_e32 v28, 0, v231, vcc
	v_sub_f32_e32 v23, v23, v28
	ds_write_b32 v109, v23 offset:56
	v_sub_f32_e32 v17, 1.0, v242
	v_fma_f32 v16, v22, v17, v242
	v_cmp_gt_f32_e32 vcc, s12, v16
	s_nop 1
	v_cndmask_b32_e64 v17, 0, 32, vcc
	v_ldexp_f32 v17, v16, v17
	v_log_f32_e32 v17, v17
	s_nop 0
	v_mul_f32_e32 v22, 0x3f317217, v17
	v_fma_f32 v22, v17, s86, -v22
	v_fmac_f32_e32 v22, 0x3377d1cf, v17
	v_fmac_f32_e32 v22, 0x3f317217, v17
	v_cmp_lt_f32_e64 s[0:1], |v17|, s87
	s_nop 1
	v_cndmask_b32_e64 v17, v17, v22, s[0:1]
	v_cndmask_b32_e32 v22, 0, v231, vcc
	v_sub_f32_e32 v17, v17, v22
	ds_write_b32 v109, v17 offset:60
	v_ashrrev_i32_e32 v17, 7, v113
	v_and_b32_e32 v22, 0x7f, v113
	v_lshlrev_b32_e32 v23, 13, v17
	v_lshlrev_b32_e32 v28, 2, v22
	v_add3_u32 v113, 0, v28, v23
	s_mov_b64 s[0:1], -1
	s_and_b64 vcc, exec, s[18:19]
	s_waitcnt lgkmcnt(0)
	s_barrier
	s_cbranch_vccz .LBB0_739
	ds_read2st64_b32 v[166:167], v113 offset0:28 offset1:30
	ds_read2st64_b32 v[168:169], v113 offset0:24 offset1:26
	ds_read2st64_b32 v[170:171], v113 offset0:20 offset1:22
	ds_read2st64_b32 v[172:173], v113 offset0:16 offset1:18
	ds_read2st64_b32 v[174:175], v113 offset0:12 offset1:14
	ds_read2st64_b32 v[176:177], v113 offset0:8 offset1:10
	ds_read2st64_b32 v[178:179], v113 offset0:4 offset1:6
	ds_read2st64_b32 v[180:181], v113 offset1:2
	s_mov_b64 s[0:1], 0
	s_waitcnt lgkmcnt(0)
	v_add_f32_e32 v29, 0, v167
	v_add_f32_e32 v119, v29, v166
	ds_write2st64_b32 v113, v119, v29 offset0:28 offset1:30
	v_add_f32_e32 v29, v119, v169
	v_add_f32_e32 v119, v29, v168
	ds_write2st64_b32 v113, v119, v29 offset0:24 offset1:26
	v_add_f32_e32 v29, v119, v171
	v_add_f32_e32 v119, v29, v170
	ds_write2st64_b32 v113, v119, v29 offset0:20 offset1:22
	v_add_f32_e32 v29, v119, v173
	v_add_f32_e32 v119, v29, v172
	ds_write2st64_b32 v113, v119, v29 offset0:16 offset1:18
	v_add_f32_e32 v29, v119, v175
	v_add_f32_e32 v119, v29, v174
	ds_write2st64_b32 v113, v119, v29 offset0:12 offset1:14
	v_add_f32_e32 v29, v119, v177
	v_add_f32_e32 v119, v29, v176
	ds_write2st64_b32 v113, v119, v29 offset0:8 offset1:10
	v_add_f32_e32 v29, v119, v179
	v_add_f32_e32 v119, v29, v178
	ds_write2st64_b32 v113, v119, v29 offset0:4 offset1:6
	v_add_f32_e32 v29, v119, v181
	v_add_f32_e32 v30, v29, v180
	ds_write2st64_b32 v113, v30, v29 offset1:2
